# re-measure: P2 order swap for half the workgroups + attention end-of-PV wait leaves MIX stores in flight
# baseline (speedup 1.0000x reference)
;     __host__ __device__ bool next(int i, Unit& u) const { const bool ok = StaticOrder::next(i, u); if (ok) u.pm = nM - 1 - u.pm; return ok; }
;     __host__ __device__ bool next(int i, Unit& u) const {
;         const long L = (long)i * G + c; if (L >= nwg) return false;
;         int wgid = (int)L; { const int q = nwg / NXCD, r = nwg % NXCD, xcd = wgid % NXCD, off = wgid / NXCD; wgid = (xcd < r ? xcd * (q + 1) : r * (q + 1) + (xcd - r) * q) + off; }
;         const int nig = wgm * nN, gid = wgid / nig, fm = gid * wgm, gsz = (nM % wgm == 0) ? wgm : ((nM - fm) < wgm ? (nM - fm) : wgm);
;         u.pm = fm + ((wgid % nig) % gsz); u.pn = (wgid % nig) / gsz; return true;
; __global__ void __launch_bounds__(NWAVES * 64, 2) fwd_megakernel(Args args) {
;     ...
;     if (IN(5)) {
;         pg8::Gemm g{F.ACT, F.Wdn_t, M, D, FF}; pg8::StaticOrder S; S.init(M, D, F.G, (int)blockIdx.x);
;         pg8::EpiDown E{F.XB, F.out};
;         pg8::gemm_phase<pg8::EpiDown, pg8::StaticOrder, true, PG8_SP2>(F.lds + RING_OFF, g, S, E, F.wave);
.LBB0_549:
	s_cmp_lt_i32 s30, 6
	s_cselect_b64 s[0:1], -1, 0
	s_cmp_gt_i32 s31, 5
	s_cselect_b64 s[4:5], -1, 0
	s_and_b64 s[0:1], s[0:1], s[4:5]
	s_andn2_b64 vcc, exec, s[0:1]
	s_cbranch_vccnz .LBB0_578
	s_andn2_b32 s33, s33, 63
	s_waitcnt vmcnt(5)
	v_mbcnt_hi_u32_b32 v0, -1, v167
	v_add_u32_e32 v0, s33, v0
	s_cmpk_gt_i32 s2, 0x3ff
	v_readfirstlane_b32 s4, v0
	s_cbranch_scc1 .LBB0_578
	s_bfe_u32 s98, s2, 0x10003
	s_cmp_eq_u32 s98, 0
	s_cbranch_scc1 .LskewP5_done
.LskewP5_loop:
	s_sleep 32
	s_sleep 32
	s_sleep 32
	s_sleep 32
	s_sleep 32
	s_sleep 32
	s_sleep 32
	s_sleep 32
	s_add_i32 s98, s98, -1
	s_cmp_lg_u32 s98, 0
	s_cbranch_scc1 .LskewP5_loop
.LskewP5_done:
	s_ashr_i32 s28, s2, 31
	s_lshr_b32 s0, s28, 29
	s_add_i32 s7, s2, s0
	s_and_b32 s0, s7, -8
	s_sub_i32 s6, s2, s0
	s_cmp_gt_i32 s6, -1
	s_cbranch_scc0 .LBB0_553
	s_lshl_b32 s5, s6, 7
	s_ashr_i32 s1, s7, 3
	s_cbranch_execz .LBB0_554
	s_branch .LBB0_555
